# diff-attention flash loop: waves 4-7 start each key-tile step ~190 cycles later (stagger between SIMD partner waves)
# speedup vs baseline: 1.0601x; 1.0056x over previous
;     ...
;                 for (int r = 0; r < 16; ++r) { s0[r] = __builtin_amdgcn_exp2f(s0[r] - mnew); s1[r] = __builtin_amdgcn_exp2f(s1[r] - mnew); ps += s0[r] + s1[r]; }
;             } else {
; #pragma unroll
;                 for (int r = 0; r < 16; ++r) { s0[r] = __builtin_amdgcn_exp2f(fmaf(s0[r], C2S, -mnew)); s1[r] = __builtin_amdgcn_exp2f(fmaf(s1[r], C2S, -mnew)); ps += s0[r] + s1[r]; }
;             }
;             lsum = lsum * alpha_l + ps;
;     ...
;         __syncthreads();
.LBB0_623:
	v_add_f32_e32 v187, v64, v80
	v_add_f32_e32 v187, 0, v187
	v_add_f32_e32 v191, v65, v81
	v_add_f32_e32 v187, v191, v187
	v_add_f32_e32 v191, v66, v82
	v_add_f32_e32 v187, v191, v187
	v_add_f32_e32 v191, v67, v83
	v_add_f32_e32 v187, v191, v187
	v_add_f32_e32 v191, v68, v84
	v_add_f32_e32 v187, v191, v187
	v_add_f32_e32 v191, v69, v85
	v_add_f32_e32 v187, v191, v187
	v_add_f32_e32 v191, v70, v86
	v_add_f32_e32 v187, v191, v187
	v_add_f32_e32 v191, v71, v87
	v_add_f32_e32 v187, v191, v187
	v_add_f32_e32 v191, v72, v88
	v_add_f32_e32 v187, v191, v187
	v_add_f32_e32 v191, v73, v89
	v_add_f32_e32 v187, v191, v187
	v_add_f32_e32 v191, v74, v90
	v_add_f32_e32 v187, v191, v187
	v_add_f32_e32 v191, v75, v91
	v_add_f32_e32 v187, v191, v187
	v_add_f32_e32 v191, v76, v92
	v_add_f32_e32 v187, v191, v187
	v_add_f32_e32 v191, v77, v93
	v_add_f32_e32 v187, v191, v187
	v_add_f32_e32 v191, v78, v94
	v_add_f32_e32 v187, v191, v187
	v_add_f32_e32 v191, v79, v95
	v_add_f32_e32 v187, v191, v187
	v_fmac_f32_e32 v187, v190, v188
	s_and_b64 vcc, exec, s[42:43]
	s_waitcnt lgkmcnt(0)
	s_barrier
	v_readfirstlane_b32 s100, v194
	s_bitcmp1_b32 s100, 8
	s_cbranch_scc0 .Lda_stag0
	s_sleep 3

; #define FA_LOADK(t) do { const int rg_ = tile_row(t); if (SPLIT) { kreg = *(const u32x4*)(Kg + (size_t)(rg_ + (tid >> 4)) * 1024 + (tid & 15) * 8); kreg2 = *(const u32x4*)(Kg + (size_t)(rg_ + 32 + (tid >> 4)) * 1024 + (tid & 15) * 8); } \
;         else kreg = *(const u32x4*)(Kg + (size_t)(rg_ + krow) * 1024 + kch * 8); } while (0)
;     ...
;     auto tile_row = [&](int t) { return t < nlat ? lat_row0 + 64 * t : ctx_row0 + 64 * (t - nlat); };
;     ...
;         if (t + 2 < nt) FA_LOADK(t + 2);
.Lda_stag0:
	s_cbranch_vccnz .LBB0_637
	s_cmp_lt_u32 s82, s52
	s_cselect_b64 s[16:17], -1, 0
	s_cmp_ge_u32 s82, s52
	s_cbranch_scc1 .LBB0_626
	s_cmp_lt_u32 s82, s80
	s_cselect_b32 s2, 0, s80
	s_cselect_b32 s3, s81, s79
	s_lshl_b32 s2, s2, 6
	s_sub_i32 s2, s3, s2
	v_add_u32_e32 v64, s2, v185
	v_subrev_u32_e32 v66, 32, v64
	v_ashrrev_i32_e32 v67, 31, v66
	v_lshlrev_b64 v[66:67], 11, v[66:67]
	v_ashrrev_i32_e32 v65, 31, v64
	v_lshl_add_u64 v[66:67], v[162:163], 0, v[66:67]
	v_lshlrev_b64 v[64:65], 11, v[64:65]
	v_lshl_add_u64 v[64:65], v[162:163], 0, v[64:65]
	global_load_dwordx4 v[152:155], v[66:67], off
	global_load_dwordx4 v[156:159], v[64:65], off

;     ...
;                 for (int r = 0; r < 16; ++r) { s0[r] = __builtin_amdgcn_exp2f(s0[r] - mnew); s1[r] = __builtin_amdgcn_exp2f(s1[r] - mnew); ps += s0[r] + s1[r]; }
;             } else {
; #pragma unroll
;                 for (int r = 0; r < 16; ++r) { s0[r] = __builtin_amdgcn_exp2f(fmaf(s0[r], C2S, -mnew)); s1[r] = __builtin_amdgcn_exp2f(fmaf(s1[r], C2S, -mnew)); ps += s0[r] + s1[r]; }
;             }
;             lsum = lsum * alpha_l + ps;
;     ...
;         __syncthreads();
.LBB0_636:
	v_add_f32_e32 v96, v96, v101
	v_add_f32_e32 v96, 0, v96
	v_add_f32_e32 v97, v97, v105
	v_add_f32_e32 v96, v97, v96
	v_add_f32_e32 v97, v98, v106
	v_add_f32_e32 v96, v97, v96
	v_add_f32_e32 v97, v99, v107
	v_add_f32_e32 v96, v97, v96
	v_add_f32_e32 v97, v100, v112
	v_add_f32_e32 v96, v97, v96
	v_add_f32_e32 v97, v102, v113
	v_add_f32_e32 v96, v97, v96
	v_add_f32_e32 v97, v103, v114
	v_add_f32_e32 v96, v97, v96
	v_add_f32_e32 v97, v104, v115
	v_add_f32_e32 v96, v97, v96
	v_add_f32_e32 v97, v108, v120
	v_add_f32_e32 v96, v97, v96
	v_add_f32_e32 v97, v109, v121
	v_add_f32_e32 v96, v97, v96
	v_add_f32_e32 v97, v110, v122
	v_add_f32_e32 v96, v97, v96
	v_add_f32_e32 v97, v111, v123
	v_add_f32_e32 v96, v97, v96
	v_add_f32_e32 v97, v116, v124
	v_add_f32_e32 v96, v97, v96
	v_add_f32_e32 v97, v117, v125
	v_add_f32_e32 v96, v97, v96
	v_add_f32_e32 v97, v118, v126
	v_add_f32_e32 v96, v97, v96
	v_add_f32_e32 v97, v119, v127
	v_add_f32_e32 v96, v97, v96
	v_fmac_f32_e32 v96, v187, v189
	v_mov_b32_e32 v187, v96
	s_waitcnt lgkmcnt(0)
	s_barrier
	v_readfirstlane_b32 s100, v194
	s_bitcmp1_b32 s100, 8
	s_cbranch_scc0 .Lda_stag1
	s_sleep 3

;     ...
;     for (int t = 0; t < nt; t += 2) {
;         step(sA0, sA1, sB0, sB1, t);
;         if (t + 1 < nt) step(sB0, sB1, sA0, sA1, t + 1);
;     }
.Lda_stag1:
	s_add_i32 s82, s82, 2
	s_cmp_ge_u32 s4, s52
	v_add_u32_e32 v185, 0x80, v185
	s_cbranch_scc0 .LBB0_638
	s_branch .LBB0_639
